# p0a pool fold: 64-term dot product loads issued in 4 batches of 16 with two batches in flight instead of 8 serialized load-wait-fma trips
# speedup vs baseline: 1.0116x; 1.0116x over previous
.LBB7_171:
	v_and_b32_e32 v4, 0x3ff, v13
	v_lshlrev_b32_e32 v8, 2, v4
	v_ashrrev_i32_e32 v4, 18, v15
	v_lshlrev_b32_e32 v0, 2, v15
	v_ashrrev_i32_e32 v5, 31, v4
	v_and_b32_e32 v0, 0xc0000, v0
	v_lshrrev_b32_e32 v9, 16, v15
	s_waitcnt vmcnt(16)
	v_lshlrev_b32_e32 v19, 2, v4
	v_lshlrev_b64 v[6:7], 22, v[4:5]
	v_lshlrev_b32_e32 v10, 8, v4
	v_or3_b32 v6, v6, v0, v8
	v_and_or_b32 v8, v9, 3, v19
	v_ashrrev_i32_e32 v11, 31, v10
	v_ashrrev_i32_e32 v9, 31, v8
	v_lshrrev_b32_e32 v17, 2, v15
	v_lshrrev_b32_e32 v18, 8, v15
	v_lshlrev_b64 v[8:9], 14, v[8:9]
	v_lshlrev_b64 v[10:11], 2, v[10:11]
	v_and_or_b32 v8, v17, s24, v8
	v_and_or_b32 v10, v18, s25, v10
	v_lshrrev_b32_e32 v16, 10, v15
	s_waitcnt lgkmcnt(0)
	v_lshl_add_u64 v[6:7], s[12:13], 0, v[6:7]
	v_lshl_add_u64 v[8:9], s[8:9], 0, v[8:9]
	v_lshl_add_u64 v[10:11], s[10:11], 0, v[10:11]
	v_mov_b32_e32 v0, 0
	s_mov_b64 s[16:17], 0x181000
	v_lshl_add_u64 v[34:35], v[6:7], 0, s[16:17]
	s_mov_b64 s[16:17], 0x2000
	global_load_dwordx4 v[44:47], v[8:9], off offset:0
	global_load_dwordx4 v[48:51], v[8:9], off offset:16
	global_load_dwordx4 v[52:55], v[8:9], off offset:32
	global_load_dwordx4 v[56:59], v[8:9], off offset:48
	global_load_dwordx4 v[60:63], v[10:11], off offset:0
	global_load_dwordx4 v[64:67], v[10:11], off offset:16
	global_load_dwordx4 v[68:71], v[10:11], off offset:32
	global_load_dwordx4 v[72:75], v[10:11], off offset:48
	global_load_dword v76, v[34:35], off offset:-4096
	global_load_dword v77, v[34:35], off
	v_lshl_add_u64 v[34:35], v[34:35], 0, s[16:17]
	global_load_dword v78, v[34:35], off offset:-4096
	global_load_dword v79, v[34:35], off
	v_lshl_add_u64 v[34:35], v[34:35], 0, s[16:17]
	global_load_dword v80, v[34:35], off offset:-4096
	global_load_dword v81, v[34:35], off
	v_lshl_add_u64 v[34:35], v[34:35], 0, s[16:17]
	global_load_dword v82, v[34:35], off offset:-4096
	global_load_dword v83, v[34:35], off
	v_lshl_add_u64 v[34:35], v[34:35], 0, s[16:17]
	global_load_dword v84, v[34:35], off offset:-4096
	global_load_dword v85, v[34:35], off
	v_lshl_add_u64 v[34:35], v[34:35], 0, s[16:17]
	global_load_dword v86, v[34:35], off offset:-4096
	global_load_dword v87, v[34:35], off
	v_lshl_add_u64 v[34:35], v[34:35], 0, s[16:17]
	global_load_dword v88, v[34:35], off offset:-4096
	global_load_dword v89, v[34:35], off
	v_lshl_add_u64 v[34:35], v[34:35], 0, s[16:17]
	global_load_dword v90, v[34:35], off offset:-4096
	global_load_dword v91, v[34:35], off
	v_lshl_add_u64 v[34:35], v[34:35], 0, s[16:17]
	global_load_dwordx4 v[92:95], v[8:9], off offset:64
	global_load_dwordx4 v[96:99], v[8:9], off offset:80
	global_load_dwordx4 v[100:103], v[8:9], off offset:96
	global_load_dwordx4 v[104:107], v[8:9], off offset:112
	global_load_dwordx4 v[108:111], v[10:11], off offset:64
	global_load_dwordx4 v[112:115], v[10:11], off offset:80
	global_load_dwordx4 v[116:119], v[10:11], off offset:96
	global_load_dwordx4 v[120:123], v[10:11], off offset:112
	global_load_dword v124, v[34:35], off offset:-4096
	global_load_dword v125, v[34:35], off
	v_lshl_add_u64 v[34:35], v[34:35], 0, s[16:17]
	global_load_dword v126, v[34:35], off offset:-4096
	global_load_dword v127, v[34:35], off
	v_lshl_add_u64 v[34:35], v[34:35], 0, s[16:17]
	global_load_dword v128, v[34:35], off offset:-4096
	global_load_dword v129, v[34:35], off
	v_lshl_add_u64 v[34:35], v[34:35], 0, s[16:17]
	global_load_dword v130, v[34:35], off offset:-4096
	global_load_dword v131, v[34:35], off
	v_lshl_add_u64 v[34:35], v[34:35], 0, s[16:17]
	global_load_dword v132, v[34:35], off offset:-4096
	global_load_dword v133, v[34:35], off
	v_lshl_add_u64 v[34:35], v[34:35], 0, s[16:17]
	global_load_dword v134, v[34:35], off offset:-4096
	global_load_dword v135, v[34:35], off
	v_lshl_add_u64 v[34:35], v[34:35], 0, s[16:17]
	global_load_dword v136, v[34:35], off offset:-4096
	global_load_dword v137, v[34:35], off
	v_lshl_add_u64 v[34:35], v[34:35], 0, s[16:17]
	global_load_dword v138, v[34:35], off offset:-4096
	global_load_dword v139, v[34:35], off
	v_lshl_add_u64 v[34:35], v[34:35], 0, s[16:17]
	s_waitcnt vmcnt(24)
	v_mul_f32_e32 v44, v44, v60
	v_mul_f32_e32 v45, v45, v61
	v_mul_f32_e32 v46, v46, v62
	v_mul_f32_e32 v47, v47, v63
	v_mul_f32_e32 v48, v48, v64
	v_mul_f32_e32 v49, v49, v65
	v_mul_f32_e32 v50, v50, v66
	v_mul_f32_e32 v51, v51, v67
	v_mul_f32_e32 v52, v52, v68
	v_mul_f32_e32 v53, v53, v69
	v_mul_f32_e32 v54, v54, v70
	v_mul_f32_e32 v55, v55, v71
	v_mul_f32_e32 v56, v56, v72
	v_mul_f32_e32 v57, v57, v73
	v_mul_f32_e32 v58, v58, v74
	v_mul_f32_e32 v59, v59, v75
	v_fmac_f32_e32 v0, v44, v76
	v_fmac_f32_e32 v0, v45, v77
	v_fmac_f32_e32 v0, v46, v78
	v_fmac_f32_e32 v0, v47, v79
	v_fmac_f32_e32 v0, v48, v80
	v_fmac_f32_e32 v0, v49, v81
	v_fmac_f32_e32 v0, v50, v82
	v_fmac_f32_e32 v0, v51, v83
	v_fmac_f32_e32 v0, v52, v84
	v_fmac_f32_e32 v0, v53, v85
	v_fmac_f32_e32 v0, v54, v86
	v_fmac_f32_e32 v0, v55, v87
	v_fmac_f32_e32 v0, v56, v88
	v_fmac_f32_e32 v0, v57, v89
	v_fmac_f32_e32 v0, v58, v90
	v_fmac_f32_e32 v0, v59, v91
	global_load_dwordx4 v[44:47], v[8:9], off offset:128
	global_load_dwordx4 v[48:51], v[8:9], off offset:144
	global_load_dwordx4 v[52:55], v[8:9], off offset:160
	global_load_dwordx4 v[56:59], v[8:9], off offset:176
	global_load_dwordx4 v[60:63], v[10:11], off offset:128
	global_load_dwordx4 v[64:67], v[10:11], off offset:144
	global_load_dwordx4 v[68:71], v[10:11], off offset:160
	global_load_dwordx4 v[72:75], v[10:11], off offset:176
	global_load_dword v76, v[34:35], off offset:-4096
	global_load_dword v77, v[34:35], off
	v_lshl_add_u64 v[34:35], v[34:35], 0, s[16:17]
	global_load_dword v78, v[34:35], off offset:-4096
	global_load_dword v79, v[34:35], off
	v_lshl_add_u64 v[34:35], v[34:35], 0, s[16:17]
	global_load_dword v80, v[34:35], off offset:-4096
	global_load_dword v81, v[34:35], off
	v_lshl_add_u64 v[34:35], v[34:35], 0, s[16:17]
	global_load_dword v82, v[34:35], off offset:-4096
	global_load_dword v83, v[34:35], off
	v_lshl_add_u64 v[34:35], v[34:35], 0, s[16:17]
	global_load_dword v84, v[34:35], off offset:-4096
	global_load_dword v85, v[34:35], off
	v_lshl_add_u64 v[34:35], v[34:35], 0, s[16:17]
	global_load_dword v86, v[34:35], off offset:-4096
	global_load_dword v87, v[34:35], off
	v_lshl_add_u64 v[34:35], v[34:35], 0, s[16:17]
	global_load_dword v88, v[34:35], off offset:-4096
	global_load_dword v89, v[34:35], off
	v_lshl_add_u64 v[34:35], v[34:35], 0, s[16:17]
	global_load_dword v90, v[34:35], off offset:-4096
	global_load_dword v91, v[34:35], off
	v_lshl_add_u64 v[34:35], v[34:35], 0, s[16:17]
	s_waitcnt vmcnt(24)
	v_mul_f32_e32 v92, v92, v108
	v_mul_f32_e32 v93, v93, v109
	v_mul_f32_e32 v94, v94, v110
	v_mul_f32_e32 v95, v95, v111
	v_mul_f32_e32 v96, v96, v112
	v_mul_f32_e32 v97, v97, v113
	v_mul_f32_e32 v98, v98, v114
	v_mul_f32_e32 v99, v99, v115
	v_mul_f32_e32 v100, v100, v116
	v_mul_f32_e32 v101, v101, v117
	v_mul_f32_e32 v102, v102, v118
	v_mul_f32_e32 v103, v103, v119
	v_mul_f32_e32 v104, v104, v120
	v_mul_f32_e32 v105, v105, v121
	v_mul_f32_e32 v106, v106, v122
	v_mul_f32_e32 v107, v107, v123
	v_fmac_f32_e32 v0, v92, v124
	v_fmac_f32_e32 v0, v93, v125
	v_fmac_f32_e32 v0, v94, v126
	v_fmac_f32_e32 v0, v95, v127
	v_fmac_f32_e32 v0, v96, v128
	v_fmac_f32_e32 v0, v97, v129
	v_fmac_f32_e32 v0, v98, v130
	v_fmac_f32_e32 v0, v99, v131
	v_fmac_f32_e32 v0, v100, v132
	v_fmac_f32_e32 v0, v101, v133
	v_fmac_f32_e32 v0, v102, v134
	v_fmac_f32_e32 v0, v103, v135
	v_fmac_f32_e32 v0, v104, v136
	v_fmac_f32_e32 v0, v105, v137
	v_fmac_f32_e32 v0, v106, v138
	v_fmac_f32_e32 v0, v107, v139
	global_load_dwordx4 v[92:95], v[8:9], off offset:192
	global_load_dwordx4 v[96:99], v[8:9], off offset:208
	global_load_dwordx4 v[100:103], v[8:9], off offset:224
	global_load_dwordx4 v[104:107], v[8:9], off offset:240
	global_load_dwordx4 v[108:111], v[10:11], off offset:192
	global_load_dwordx4 v[112:115], v[10:11], off offset:208
	global_load_dwordx4 v[116:119], v[10:11], off offset:224
	global_load_dwordx4 v[120:123], v[10:11], off offset:240
	global_load_dword v124, v[34:35], off offset:-4096
	global_load_dword v125, v[34:35], off
	v_lshl_add_u64 v[34:35], v[34:35], 0, s[16:17]
	global_load_dword v126, v[34:35], off offset:-4096
	global_load_dword v127, v[34:35], off
	v_lshl_add_u64 v[34:35], v[34:35], 0, s[16:17]
	global_load_dword v128, v[34:35], off offset:-4096
	global_load_dword v129, v[34:35], off
	v_lshl_add_u64 v[34:35], v[34:35], 0, s[16:17]
	global_load_dword v130, v[34:35], off offset:-4096
	global_load_dword v131, v[34:35], off
	v_lshl_add_u64 v[34:35], v[34:35], 0, s[16:17]
	global_load_dword v132, v[34:35], off offset:-4096
	global_load_dword v133, v[34:35], off
	v_lshl_add_u64 v[34:35], v[34:35], 0, s[16:17]
	global_load_dword v134, v[34:35], off offset:-4096
	global_load_dword v135, v[34:35], off
	v_lshl_add_u64 v[34:35], v[34:35], 0, s[16:17]
	global_load_dword v136, v[34:35], off offset:-4096
	global_load_dword v137, v[34:35], off
	v_lshl_add_u64 v[34:35], v[34:35], 0, s[16:17]
	global_load_dword v138, v[34:35], off offset:-4096
	global_load_dword v139, v[34:35], off
	v_lshl_add_u64 v[34:35], v[34:35], 0, s[16:17]
	s_waitcnt vmcnt(24)
	v_mul_f32_e32 v44, v44, v60
	v_mul_f32_e32 v45, v45, v61
	v_mul_f32_e32 v46, v46, v62
	v_mul_f32_e32 v47, v47, v63
	v_mul_f32_e32 v48, v48, v64
	v_mul_f32_e32 v49, v49, v65
	v_mul_f32_e32 v50, v50, v66
	v_mul_f32_e32 v51, v51, v67
	v_mul_f32_e32 v52, v52, v68
	v_mul_f32_e32 v53, v53, v69
	v_mul_f32_e32 v54, v54, v70
	v_mul_f32_e32 v55, v55, v71
	v_mul_f32_e32 v56, v56, v72
	v_mul_f32_e32 v57, v57, v73
	v_mul_f32_e32 v58, v58, v74
	v_mul_f32_e32 v59, v59, v75
	v_fmac_f32_e32 v0, v44, v76
	v_fmac_f32_e32 v0, v45, v77
	v_fmac_f32_e32 v0, v46, v78
	v_fmac_f32_e32 v0, v47, v79
	v_fmac_f32_e32 v0, v48, v80
	v_fmac_f32_e32 v0, v49, v81
	v_fmac_f32_e32 v0, v50, v82
	v_fmac_f32_e32 v0, v51, v83
	v_fmac_f32_e32 v0, v52, v84
	v_fmac_f32_e32 v0, v53, v85
	v_fmac_f32_e32 v0, v54, v86
	v_fmac_f32_e32 v0, v55, v87
	v_fmac_f32_e32 v0, v56, v88
	v_fmac_f32_e32 v0, v57, v89
	v_fmac_f32_e32 v0, v58, v90
	v_fmac_f32_e32 v0, v59, v91
	s_waitcnt vmcnt(0)
	v_mul_f32_e32 v92, v92, v108
	v_mul_f32_e32 v93, v93, v109
	v_mul_f32_e32 v94, v94, v110
	v_mul_f32_e32 v95, v95, v111
	v_mul_f32_e32 v96, v96, v112
	v_mul_f32_e32 v97, v97, v113
	v_mul_f32_e32 v98, v98, v114
	v_mul_f32_e32 v99, v99, v115
	v_mul_f32_e32 v100, v100, v116
	v_mul_f32_e32 v101, v101, v117
	v_mul_f32_e32 v102, v102, v118
	v_mul_f32_e32 v103, v103, v119
	v_mul_f32_e32 v104, v104, v120
	v_mul_f32_e32 v105, v105, v121
	v_mul_f32_e32 v106, v106, v122
	v_mul_f32_e32 v107, v107, v123
	v_fmac_f32_e32 v0, v92, v124
	v_fmac_f32_e32 v0, v93, v125
	v_fmac_f32_e32 v0, v94, v126
	v_fmac_f32_e32 v0, v95, v127
	v_fmac_f32_e32 v0, v96, v128
	v_fmac_f32_e32 v0, v97, v129
	v_fmac_f32_e32 v0, v98, v130
	v_fmac_f32_e32 v0, v99, v131
	v_fmac_f32_e32 v0, v100, v132
	v_fmac_f32_e32 v0, v101, v133
	v_fmac_f32_e32 v0, v102, v134
	v_fmac_f32_e32 v0, v103, v135
	v_fmac_f32_e32 v0, v104, v136
	v_fmac_f32_e32 v0, v105, v137
	v_fmac_f32_e32 v0, v106, v138
	v_fmac_f32_e32 v0, v107, v139
	v_and_b32_e32 v6, 0x3ff, v15
	v_cvt_pk_bf16_f32 v7, v0, v1
	v_mad_i64_i32 v[4:5], s[16:17], v4, s30, v[2:3]
	v_lshlrev_b32_e32 v0, 11, v6
	v_lshl_add_u64 v[4:5], v[4:5], 0, v[0:1]
	v_lshlrev_b32_sdwa v0, v14, v16 dst_sel:DWORD dst_unused:UNUSED_PAD src0_sel:DWORD src1_sel:BYTE_0
	v_lshl_add_u64 v[4:5], v[4:5], 0, v[0:1]
	v_add_co_u32_e32 v4, vcc, 0x2500000, v4
	v_add_u32_e32 v15, s33, v15
	s_nop 0
	v_addc_co_u32_e32 v5, vcc, 0, v5, vcc
	v_cmp_lt_i32_e32 vcc, s31, v15
	s_or_b64 s[14:15], vcc, s[14:15]
	v_subrev_u16_e32 v13, s33, v13
	global_store_short v[4:5], v7, off offset:768
	s_andn2_b64 exec, exec, s[14:15]
	s_cbranch_execnz .LBB7_171
